# baseline (speedup 1.0000x reference)
; __device__ __forceinline__ void ssm_disc(ArgP a, int l, int g, int p, float& ar, float& ai, float& zr, float& zi) {
;     const float dt = expf(a->log_dt[l * 32 + g]);
;     const float lr = a->lam_re[((size_t)l * 32 + g) * 64 + p], li = a->lam_im[((size_t)l * 32 + g) * 64 + p];
;     const float mag = expf(lr * dt), th = li * dt;
;     ar = mag * cosf(th); ai = mag * sinf(th);
;     const float den = lr * lr + li * li, nr = ar - 1.f, ni = ai;
;     zr = (nr * lr + ni * li) / den; zi = (ni * lr - nr * li) / den;
; __device__ __forceinline__ void ssm_pass2(ArgP a, LAS unsigned char* lds, int l, const int tid, const int item) {
;     ...
;         float ar, ai, zr, zi; ssm_disc(a, l, g, lane, ar, ai, zr, zi);
;         float pr = ar, pi = ai;
; #pragma unroll
;         for (int s = 0; s < 8; ++s) { const float nr = pr * pr - pi * pi, ni = 2.f * pr * pi; pr = nr; pi = ni; }
;         float wr_ = 0.f, wi_ = 0.f;
;         { typedef float f32x2e __attribute__((ext_vector_type(2)));
;           const f32x2e* eb = (const f32x2e*)(E + ((size_t)g * 64 + lane) * 2);
;           int j = 0;
;           for (; j + 8 <= chunk; j += 8) { f32x2e ev[8];
; #pragma unroll
;               for (int q = 0; q < 8; ++q) ev[q] = eb[(size_t)(j + q) * (32 * 64)];
; #pragma unroll
;               for (int q = 0; q < 8; ++q) { const float nr = fmaf(pr, wr_, fmaf(-pi, wi_, ev[q].x)), ni = fmaf(pr, wi_, fmaf(pi, wr_, ev[q].y)); wr_ = nr; wi_ = ni; } }
;           for (; j < chunk; ++j) { const f32x2e ev = eb[(size_t)j * (32 * 64)];
;               const float nr = fmaf(pr, wr_, fmaf(-pi, wi_, ev.x)), ni = fmaf(pr, wi_, fmaf(pi, wr_, ev.y)); wr_ = nr; wi_ = ni; } }
.LBB0_159:
	s_or_b64 exec, exec, s[0:1]
	s_waitcnt vmcnt(0)
	v_mul_f32_e32 v2, v3, v2
	v_mul_f32_e32 v3, 0x3fb8aa3b, v2
	s_mov_b32 s0, 0x3fb8aa3b
	v_fma_f32 v6, v2, s0, -v3
	v_rndne_f32_e32 v7, v3
	v_fmac_f32_e32 v6, 0x32a5705f, v2
	v_sub_f32_e32 v3, v3, v7
	v_add_f32_e32 v3, v3, v6
	v_cvt_i32_f32_e32 v6, v7
	v_exp_f32_e32 v3, v3
	s_mov_b32 s0, 0xc2ce8ed0
	v_cmp_ngt_f32_e32 vcc, s0, v2
	s_mov_b32 s0, 0x42b17218
	v_ldexp_f32 v3, v3, v6
	v_cndmask_b32_e32 v3, 0, v3, vcc
	v_cmp_nlt_f32_e32 vcc, s0, v2
	v_mov_b32_e32 v7, 0x3c0881c4
	s_brev_b32 s0, 1
	v_cndmask_b32_e32 v2, v201, v3, vcc
	v_mul_f32_e32 v3, v5, v5
	v_fmamk_f32 v6, v3, 0xb94c1982, v7
	v_fmaak_f32 v6, v3, v6, 0xbe2aaa9d
	v_mul_f32_e32 v6, v3, v6
	v_fmac_f32_e32 v5, v5, v6
	v_fmamk_f32 v6, v3, 0x37d75334, v202
	v_fmaak_f32 v6, v3, v6, 0x3d2aabf7
	v_fmaak_f32 v6, v3, v6, 0xbf000004
	v_fma_f32 v3, v3, v6, 1.0
	v_and_b32_e32 v6, 1, v4
	v_cmp_eq_u32_e32 vcc, 0, v6
	v_lshlrev_b32_e32 v4, 30, v4
	s_mov_b32 s86, 0
	v_cndmask_b32_e64 v3, -v5, v3, vcc
	v_bitop3_b32 v3, v4, v3, s0 bitop3:0x6c
	s_movk_i32 s0, 0x1f8
	v_cmp_class_f32_e64 vcc, v0, s0
	v_xor_b32_e32 v0, v1, v0
	s_ashr_i32 s0, s55, 2
	v_cndmask_b32_e32 v3, v204, v3, vcc
	v_mul_f32_e32 v20, v2, v3
	v_mul_f32_e32 v3, v9, v9
	v_fmamk_f32 v4, v3, 0xb94c1982, v7
	v_fmaak_f32 v4, v3, v4, 0xbe2aaa9d
	v_mul_f32_e32 v4, v3, v4
	v_fmac_f32_e32 v9, v9, v4
	v_fmamk_f32 v4, v3, 0x37d75334, v202
	v_fmaak_f32 v4, v3, v4, 0x3d2aabf7
	v_fmaak_f32 v4, v3, v4, 0xbf000004
	v_fma_f32 v3, v3, v4, 1.0
	v_and_b32_e32 v4, 1, v8
	v_cmp_eq_u32_e64 s[6:7], 0, v4
	v_lshlrev_b32_e32 v4, 30, v8
	v_and_b32_e32 v4, 0x80000000, v4
	v_cndmask_b32_e64 v3, v3, v9, s[6:7]
	v_xor_b32_e32 v0, v0, v4
	v_xor_b32_e32 v0, v0, v3
	v_cndmask_b32_e32 v0, v204, v0, vcc
	v_mul_f32_e32 v22, v2, v0
	v_add_f32_e32 v1, v20, v20
	v_mul_f32_e32 v0, v22, v22
	v_mul_f32_e32 v1, v1, v22
	v_fma_f32 v0, v20, v20, -v0
	v_mul_f32_e32 v2, v1, v1
	v_fma_f32 v2, v0, v0, -v2
	v_add_f32_e32 v0, v0, v0
	v_mul_f32_e32 v0, v1, v0
	v_mul_f32_e32 v1, v0, v0
	v_fma_f32 v1, v2, v2, -v1
	v_add_f32_e32 v2, v2, v2
	v_mul_f32_e32 v0, v0, v2
	v_mul_f32_e32 v2, v0, v0
	v_fma_f32 v2, v1, v1, -v2
	v_add_f32_e32 v1, v1, v1
	v_mul_f32_e32 v0, v0, v1
	v_mul_f32_e32 v1, v0, v0
	v_fma_f32 v1, v2, v2, -v1
	v_add_f32_e32 v2, v2, v2
	v_mul_f32_e32 v0, v0, v2
	v_mul_f32_e32 v2, v0, v0
	v_fma_f32 v2, v1, v1, -v2
	v_add_f32_e32 v1, v1, v1
	v_mul_f32_e32 v0, v0, v1
	v_mul_f32_e32 v1, v0, v0
	v_fma_f32 v1, v2, v2, -v1
	v_add_f32_e32 v2, v2, v2
	v_mul_f32_e32 v2, v0, v2
	v_mul_f32_e32 v0, v2, v2
	v_fma_f32 v0, v1, v1, -v0
	v_add_f32_e32 v1, v1, v1
	v_mul_f32_e32 v3, v2, v1
	v_xor_b32_e32 v2, 0x80000000, v3
	v_lshlrev_b32_e32 v4, 3, v16
	v_mov_b32_e32 v1, v0
	v_mov_b32_e32 v24, 0
	v_mov_b32_e32 v25, 0
	s_cmp_lt_i32 s0, 1
	s_cbranch_scc1 .LBB0_167
	s_and_b32 s1, s55, 3
	s_lshl_b32 s1, s1, 12
	s_ashr_i32 s5, s4, 31
	s_lshl_b64 s[8:9], s[4:5], 9
	s_add_u32 s1, s1, s8
	s_addc_u32 s5, 0, s9
	s_add_u32 s6, s53, s1
	s_addc_u32 s7, s54, s5
	global_load_dwordx2 v[50:51], v4, s[6:7]
	s_cmp_eq_u32 s0, 1
	s_cbranch_scc1 .Lscan_chain
	s_add_u32 s6, s6, 0x4000
	s_addc_u32 s7, s7, 0
	global_load_dwordx2 v[52:53], v4, s[6:7]
	s_cmp_eq_u32 s0, 2
	s_cbranch_scc1 .Lscan_chain
	s_add_u32 s6, s6, 0x4000
	s_addc_u32 s7, s7, 0
	global_load_dwordx2 v[54:55], v4, s[6:7]
	s_cmp_eq_u32 s0, 3
	s_cbranch_scc1 .Lscan_chain
	s_add_u32 s6, s6, 0x4000
	s_addc_u32 s7, s7, 0
	global_load_dwordx2 v[56:57], v4, s[6:7]
	s_cmp_eq_u32 s0, 4
	s_cbranch_scc1 .Lscan_chain
	s_add_u32 s6, s6, 0x4000
	s_addc_u32 s7, s7, 0
	global_load_dwordx2 v[58:59], v4, s[6:7]
	s_cmp_eq_u32 s0, 5
	s_cbranch_scc1 .Lscan_chain
	s_add_u32 s6, s6, 0x4000
	s_addc_u32 s7, s7, 0
	global_load_dwordx2 v[60:61], v4, s[6:7]
	s_cmp_eq_u32 s0, 6
	s_cbranch_scc1 .Lscan_chain
	s_add_u32 s6, s6, 0x4000
	s_addc_u32 s7, s7, 0
	global_load_dwordx2 v[62:63], v4, s[6:7]
	s_cmp_eq_u32 s0, 7
	s_cbranch_scc1 .Lscan_chain
	s_add_u32 s6, s6, 0x4000
	s_addc_u32 s7, s7, 0
	global_load_dwordx2 v[64:65], v4, s[6:7]
	s_cmp_eq_u32 s0, 8
	s_cbranch_scc1 .Lscan_chain
	s_add_u32 s6, s6, 0x4000
	s_addc_u32 s7, s7, 0
	global_load_dwordx2 v[66:67], v4, s[6:7]
	s_cmp_eq_u32 s0, 9
	s_cbranch_scc1 .Lscan_chain
	s_add_u32 s6, s6, 0x4000
	s_addc_u32 s7, s7, 0
	global_load_dwordx2 v[68:69], v4, s[6:7]
	s_cmp_eq_u32 s0, 10
	s_cbranch_scc1 .Lscan_chain
	s_add_u32 s6, s6, 0x4000
	s_addc_u32 s7, s7, 0
	global_load_dwordx2 v[70:71], v4, s[6:7]
	s_cmp_eq_u32 s0, 11
	s_cbranch_scc1 .Lscan_chain
	s_add_u32 s6, s6, 0x4000
	s_addc_u32 s7, s7, 0
	global_load_dwordx2 v[72:73], v4, s[6:7]
	s_cmp_eq_u32 s0, 12
	s_cbranch_scc1 .Lscan_chain
	s_add_u32 s6, s6, 0x4000
	s_addc_u32 s7, s7, 0
	global_load_dwordx2 v[74:75], v4, s[6:7]
	s_cmp_eq_u32 s0, 13
	s_cbranch_scc1 .Lscan_chain
	s_add_u32 s6, s6, 0x4000
	s_addc_u32 s7, s7, 0
	global_load_dwordx2 v[76:77], v4, s[6:7]
	s_cmp_eq_u32 s0, 14
	s_cbranch_scc1 .Lscan_chain
	s_add_u32 s6, s6, 0x4000
	s_addc_u32 s7, s7, 0
	global_load_dwordx2 v[78:79], v4, s[6:7]
	s_cmp_eq_u32 s0, 15
	s_cbranch_scc1 .Lscan_chain
	s_add_u32 s6, s6, 0x4000
	s_addc_u32 s7, s7, 0
	global_load_dwordx2 v[80:81], v4, s[6:7]
	s_cmp_eq_u32 s0, 16
	s_cbranch_scc1 .Lscan_chain
	s_add_u32 s6, s6, 0x4000
	s_addc_u32 s7, s7, 0
	global_load_dwordx2 v[82:83], v4, s[6:7]
	s_cmp_eq_u32 s0, 17
	s_cbranch_scc1 .Lscan_chain
	s_add_u32 s6, s6, 0x4000
	s_addc_u32 s7, s7, 0
	global_load_dwordx2 v[84:85], v4, s[6:7]
	s_cmp_eq_u32 s0, 18
	s_cbranch_scc1 .Lscan_chain
	s_add_u32 s6, s6, 0x4000
	s_addc_u32 s7, s7, 0
	global_load_dwordx2 v[86:87], v4, s[6:7]
	s_cmp_eq_u32 s0, 19
	s_cbranch_scc1 .Lscan_chain
; __device__ __forceinline__ void ssm_pass2(ArgP a, LAS unsigned char* lds, int l, const int tid, const int item) {
;     ...
;         { typedef float f32x2e __attribute__((ext_vector_type(2)));
;           const f32x2e* eb = (const f32x2e*)(E + ((size_t)g * 64 + lane) * 2);
;           int j = 0;
;           for (; j + 8 <= chunk; j += 8) { f32x2e ev[8];
; #pragma unroll
;               for (int q = 0; q < 8; ++q) ev[q] = eb[(size_t)(j + q) * (32 * 64)];
; #pragma unroll
;               for (int q = 0; q < 8; ++q) { const float nr = fmaf(pr, wr_, fmaf(-pi, wi_, ev[q].x)), ni = fmaf(pr, wi_, fmaf(pi, wr_, ev[q].y)); wr_ = nr; wi_ = ni; } }
;           for (; j < chunk; ++j) { const f32x2e ev = eb[(size_t)j * (32 * 64)];
;               const float nr = fmaf(pr, wr_, fmaf(-pi, wi_, ev.x)), ni = fmaf(pr, wi_, fmaf(pi, wr_, ev.y)); wr_ = nr; wi_ = ni; } }
	s_add_u32 s6, s6, 0x4000
	s_addc_u32 s7, s7, 0
	global_load_dwordx2 v[88:89], v4, s[6:7]
	s_cmp_eq_u32 s0, 20
	s_cbranch_scc1 .Lscan_chain
	s_add_u32 s6, s6, 0x4000
	s_addc_u32 s7, s7, 0
	global_load_dwordx2 v[90:91], v4, s[6:7]
	s_cmp_eq_u32 s0, 21
	s_cbranch_scc1 .Lscan_chain
	s_add_u32 s6, s6, 0x4000
	s_addc_u32 s7, s7, 0
	global_load_dwordx2 v[92:93], v4, s[6:7]
	s_cmp_eq_u32 s0, 22
	s_cbranch_scc1 .Lscan_chain
	s_add_u32 s6, s6, 0x4000
	s_addc_u32 s7, s7, 0
	global_load_dwordx2 v[94:95], v4, s[6:7]
	s_cmp_eq_u32 s0, 23
	s_cbranch_scc1 .Lscan_chain
	s_add_u32 s6, s6, 0x4000
	s_addc_u32 s7, s7, 0
	global_load_dwordx2 v[96:97], v4, s[6:7]
	s_cmp_eq_u32 s0, 24
	s_cbranch_scc1 .Lscan_chain
	s_add_u32 s6, s6, 0x4000
	s_addc_u32 s7, s7, 0
	global_load_dwordx2 v[98:99], v4, s[6:7]
	s_cmp_eq_u32 s0, 25
	s_cbranch_scc1 .Lscan_chain
	s_add_u32 s6, s6, 0x4000
	s_addc_u32 s7, s7, 0
	global_load_dwordx2 v[100:101], v4, s[6:7]
	s_cmp_eq_u32 s0, 26
	s_cbranch_scc1 .Lscan_chain
	s_add_u32 s6, s6, 0x4000
	s_addc_u32 s7, s7, 0
	global_load_dwordx2 v[102:103], v4, s[6:7]
	s_cmp_eq_u32 s0, 27
	s_cbranch_scc1 .Lscan_chain
	s_add_u32 s6, s6, 0x4000
	s_addc_u32 s7, s7, 0
	global_load_dwordx2 v[104:105], v4, s[6:7]
	s_cmp_eq_u32 s0, 28
	s_cbranch_scc1 .Lscan_chain
	s_add_u32 s6, s6, 0x4000
	s_addc_u32 s7, s7, 0
	global_load_dwordx2 v[106:107], v4, s[6:7]
	s_cmp_eq_u32 s0, 29
	s_cbranch_scc1 .Lscan_chain
	s_add_u32 s6, s6, 0x4000
	s_addc_u32 s7, s7, 0
	global_load_dwordx2 v[108:109], v4, s[6:7]
	s_cmp_eq_u32 s0, 30
	s_cbranch_scc1 .Lscan_chain
	s_add_u32 s6, s6, 0x4000
	s_addc_u32 s7, s7, 0
	global_load_dwordx2 v[110:111], v4, s[6:7]
	s_cmp_eq_u32 s0, 31
	s_cbranch_scc1 .Lscan_chain
	s_add_u32 s6, s6, 0x4000
	s_addc_u32 s7, s7, 0
	global_load_dwordx2 v[112:113], v4, s[6:7]
	s_cmp_eq_u32 s0, 32
	s_cbranch_scc1 .Lscan_chain
	s_add_u32 s6, s6, 0x4000
	s_addc_u32 s7, s7, 0
	global_load_dwordx2 v[114:115], v4, s[6:7]
	s_cmp_eq_u32 s0, 33
	s_cbranch_scc1 .Lscan_chain
	s_add_u32 s6, s6, 0x4000
	s_addc_u32 s7, s7, 0
	global_load_dwordx2 v[116:117], v4, s[6:7]
	s_cmp_eq_u32 s0, 34
	s_cbranch_scc1 .Lscan_chain
	s_add_u32 s6, s6, 0x4000
	s_addc_u32 s7, s7, 0
	global_load_dwordx2 v[118:119], v4, s[6:7]
	s_cmp_eq_u32 s0, 35
	s_cbranch_scc1 .Lscan_chain
	s_add_u32 s6, s6, 0x4000
	s_addc_u32 s7, s7, 0
	global_load_dwordx2 v[120:121], v4, s[6:7]
	s_cmp_eq_u32 s0, 36
	s_cbranch_scc1 .Lscan_chain
	s_add_u32 s6, s6, 0x4000
	s_addc_u32 s7, s7, 0
	global_load_dwordx2 v[122:123], v4, s[6:7]
	s_cmp_eq_u32 s0, 37
	s_cbranch_scc1 .Lscan_chain
	s_add_u32 s6, s6, 0x4000
	s_addc_u32 s7, s7, 0
	global_load_dwordx2 v[124:125], v4, s[6:7]
	s_cmp_eq_u32 s0, 38
	s_cbranch_scc1 .Lscan_chain
	s_add_u32 s6, s6, 0x4000
	s_addc_u32 s7, s7, 0
	global_load_dwordx2 v[126:127], v4, s[6:7]
	s_cmp_eq_u32 s0, 39
	s_cbranch_scc1 .Lscan_chain
	s_add_u32 s6, s6, 0x4000
	s_addc_u32 s7, s7, 0
	global_load_dwordx2 v[128:129], v4, s[6:7]
	s_cmp_eq_u32 s0, 40
	s_cbranch_scc1 .Lscan_chain
	s_add_u32 s6, s6, 0x4000
	s_addc_u32 s7, s7, 0
	global_load_dwordx2 v[130:131], v4, s[6:7]
	s_cmp_eq_u32 s0, 41
	s_cbranch_scc1 .Lscan_chain
	s_add_u32 s6, s6, 0x4000
	s_addc_u32 s7, s7, 0
	global_load_dwordx2 v[132:133], v4, s[6:7]
	s_cmp_eq_u32 s0, 42
	s_cbranch_scc1 .Lscan_chain
	s_add_u32 s6, s6, 0x4000
	s_addc_u32 s7, s7, 0
	global_load_dwordx2 v[134:135], v4, s[6:7]
	s_cmp_eq_u32 s0, 43
	s_cbranch_scc1 .Lscan_chain
	s_add_u32 s6, s6, 0x4000
	s_addc_u32 s7, s7, 0
	global_load_dwordx2 v[136:137], v4, s[6:7]
	s_cmp_eq_u32 s0, 44
	s_cbranch_scc1 .Lscan_chain
	s_add_u32 s6, s6, 0x4000
	s_addc_u32 s7, s7, 0
	global_load_dwordx2 v[138:139], v4, s[6:7]
	s_cmp_eq_u32 s0, 45
	s_cbranch_scc1 .Lscan_chain
	s_add_u32 s6, s6, 0x4000
	s_addc_u32 s7, s7, 0
	global_load_dwordx2 v[140:141], v4, s[6:7]
	s_cmp_eq_u32 s0, 46
	s_cbranch_scc1 .Lscan_chain
	s_add_u32 s6, s6, 0x4000
	s_addc_u32 s7, s7, 0
	global_load_dwordx2 v[142:143], v4, s[6:7]
	s_cmp_eq_u32 s0, 47
	s_cbranch_scc1 .Lscan_chain
	s_add_u32 s6, s6, 0x4000
	s_addc_u32 s7, s7, 0
	global_load_dwordx2 v[146:147], v4, s[6:7]
	s_cmp_eq_u32 s0, 48
	s_cbranch_scc1 .Lscan_chain
	s_add_u32 s6, s6, 0x4000
	s_addc_u32 s7, s7, 0
	global_load_dwordx2 v[148:149], v4, s[6:7]
	s_cmp_eq_u32 s0, 49
	s_cbranch_scc1 .Lscan_chain
	s_add_u32 s6, s6, 0x4000
	s_addc_u32 s7, s7, 0
	global_load_dwordx2 v[150:151], v4, s[6:7]
	s_cmp_eq_u32 s0, 50
	s_cbranch_scc1 .Lscan_chain
	s_add_u32 s6, s6, 0x4000
	s_addc_u32 s7, s7, 0
	global_load_dwordx2 v[152:153], v4, s[6:7]
	s_cmp_eq_u32 s0, 51
	s_cbranch_scc1 .Lscan_chain
	s_add_u32 s6, s6, 0x4000
	s_addc_u32 s7, s7, 0
	global_load_dwordx2 v[154:155], v4, s[6:7]
	s_cmp_eq_u32 s0, 52
	s_cbranch_scc1 .Lscan_chain
	s_add_u32 s6, s6, 0x4000
	s_addc_u32 s7, s7, 0
	global_load_dwordx2 v[156:157], v4, s[6:7]
	s_cmp_eq_u32 s0, 53
	s_cbranch_scc1 .Lscan_chain
	s_add_u32 s6, s6, 0x4000
	s_addc_u32 s7, s7, 0
	global_load_dwordx2 v[158:159], v4, s[6:7]
	s_cmp_eq_u32 s0, 54
	s_cbranch_scc1 .Lscan_chain
	s_add_u32 s6, s6, 0x4000
	s_addc_u32 s7, s7, 0
	global_load_dwordx2 v[160:161], v4, s[6:7]
	s_cmp_eq_u32 s0, 55
	s_cbranch_scc1 .Lscan_chain
	s_add_u32 s6, s6, 0x4000
	s_addc_u32 s7, s7, 0
	global_load_dwordx2 v[162:163], v4, s[6:7]
	s_cmp_eq_u32 s0, 56
	s_cbranch_scc1 .Lscan_chain
	s_add_u32 s6, s6, 0x4000
	s_addc_u32 s7, s7, 0
	global_load_dwordx2 v[164:165], v4, s[6:7]
	s_cmp_eq_u32 s0, 57
	s_cbranch_scc1 .Lscan_chain
	s_add_u32 s6, s6, 0x4000
	s_addc_u32 s7, s7, 0
	global_load_dwordx2 v[166:167], v4, s[6:7]
	s_cmp_eq_u32 s0, 58
	s_cbranch_scc1 .Lscan_chain
	s_add_u32 s6, s6, 0x4000
	s_addc_u32 s7, s7, 0
	global_load_dwordx2 v[168:169], v4, s[6:7]
	s_cmp_eq_u32 s0, 59
	s_cbranch_scc1 .Lscan_chain
	s_add_u32 s6, s6, 0x4000
	s_addc_u32 s7, s7, 0
	global_load_dwordx2 v[170:171], v4, s[6:7]
	s_cmp_eq_u32 s0, 60
	s_cbranch_scc1 .Lscan_chain
	s_add_u32 s6, s6, 0x4000
	s_addc_u32 s7, s7, 0
	global_load_dwordx2 v[172:173], v4, s[6:7]
	s_cmp_eq_u32 s0, 61
	s_cbranch_scc1 .Lscan_chain
	s_add_u32 s6, s6, 0x4000
	s_addc_u32 s7, s7, 0
	global_load_dwordx2 v[174:175], v4, s[6:7]
	s_cmp_eq_u32 s0, 62
	s_cbranch_scc1 .Lscan_chain
	s_add_u32 s6, s6, 0x4000
	s_addc_u32 s7, s7, 0
	global_load_dwordx2 v[176:177], v4, s[6:7]
; __device__ __forceinline__ void ssm_pass2(ArgP a, LAS unsigned char* lds, int l, const int tid, const int item) {
;     ...
;           for (; j + 8 <= chunk; j += 8) { f32x2e ev[8];
; #pragma unroll
;               for (int q = 0; q < 8; ++q) ev[q] = eb[(size_t)(j + q) * (32 * 64)];
; #pragma unroll
;               for (int q = 0; q < 8; ++q) { const float nr = fmaf(pr, wr_, fmaf(-pi, wi_, ev[q].x)), ni = fmaf(pr, wi_, fmaf(pi, wr_, ev[q].y)); wr_ = nr; wi_ = ni; } }
;           for (; j < chunk; ++j) { const f32x2e ev = eb[(size_t)j * (32 * 64)];
;               const float nr = fmaf(pr, wr_, fmaf(-pi, wi_, ev.x)), ni = fmaf(pr, wi_, fmaf(pi, wr_, ev.y)); wr_ = nr; wi_ = ni; } }
.Lscan_chain:
	s_waitcnt vmcnt(0)
	v_pk_fma_f32 v[50:51], v[2:3], v[24:25], v[50:51] op_sel:[0,1,0] op_sel_hi:[1,0,1]
	s_nop 0
	v_pk_fma_f32 v[24:25], v[0:1], v[24:25], v[50:51]
	s_cmp_eq_u32 s0, 1
	s_cbranch_scc1 .LBB0_167
	v_pk_fma_f32 v[52:53], v[2:3], v[24:25], v[52:53] op_sel:[0,1,0] op_sel_hi:[1,0,1]
	s_nop 0
	v_pk_fma_f32 v[24:25], v[0:1], v[24:25], v[52:53]
	s_cmp_eq_u32 s0, 2
	s_cbranch_scc1 .LBB0_167
	v_pk_fma_f32 v[54:55], v[2:3], v[24:25], v[54:55] op_sel:[0,1,0] op_sel_hi:[1,0,1]
	s_nop 0
	v_pk_fma_f32 v[24:25], v[0:1], v[24:25], v[54:55]
	s_cmp_eq_u32 s0, 3
	s_cbranch_scc1 .LBB0_167
	v_pk_fma_f32 v[56:57], v[2:3], v[24:25], v[56:57] op_sel:[0,1,0] op_sel_hi:[1,0,1]
	s_nop 0
	v_pk_fma_f32 v[24:25], v[0:1], v[24:25], v[56:57]
	s_cmp_eq_u32 s0, 4
	s_cbranch_scc1 .LBB0_167
	v_pk_fma_f32 v[58:59], v[2:3], v[24:25], v[58:59] op_sel:[0,1,0] op_sel_hi:[1,0,1]
	s_nop 0
	v_pk_fma_f32 v[24:25], v[0:1], v[24:25], v[58:59]
	s_cmp_eq_u32 s0, 5
	s_cbranch_scc1 .LBB0_167
	v_pk_fma_f32 v[60:61], v[2:3], v[24:25], v[60:61] op_sel:[0,1,0] op_sel_hi:[1,0,1]
	s_nop 0
	v_pk_fma_f32 v[24:25], v[0:1], v[24:25], v[60:61]
	s_cmp_eq_u32 s0, 6
	s_cbranch_scc1 .LBB0_167
	v_pk_fma_f32 v[62:63], v[2:3], v[24:25], v[62:63] op_sel:[0,1,0] op_sel_hi:[1,0,1]
	s_nop 0
	v_pk_fma_f32 v[24:25], v[0:1], v[24:25], v[62:63]
	s_cmp_eq_u32 s0, 7
	s_cbranch_scc1 .LBB0_167
	v_pk_fma_f32 v[64:65], v[2:3], v[24:25], v[64:65] op_sel:[0,1,0] op_sel_hi:[1,0,1]
	s_nop 0
	v_pk_fma_f32 v[24:25], v[0:1], v[24:25], v[64:65]
	s_cmp_eq_u32 s0, 8
	s_cbranch_scc1 .LBB0_167
	v_pk_fma_f32 v[66:67], v[2:3], v[24:25], v[66:67] op_sel:[0,1,0] op_sel_hi:[1,0,1]
	s_nop 0
	v_pk_fma_f32 v[24:25], v[0:1], v[24:25], v[66:67]
	s_cmp_eq_u32 s0, 9
	s_cbranch_scc1 .LBB0_167
	v_pk_fma_f32 v[68:69], v[2:3], v[24:25], v[68:69] op_sel:[0,1,0] op_sel_hi:[1,0,1]
	s_nop 0
	v_pk_fma_f32 v[24:25], v[0:1], v[24:25], v[68:69]
	s_cmp_eq_u32 s0, 10
	s_cbranch_scc1 .LBB0_167
	v_pk_fma_f32 v[70:71], v[2:3], v[24:25], v[70:71] op_sel:[0,1,0] op_sel_hi:[1,0,1]
	s_nop 0
	v_pk_fma_f32 v[24:25], v[0:1], v[24:25], v[70:71]
	s_cmp_eq_u32 s0, 11
	s_cbranch_scc1 .LBB0_167
	v_pk_fma_f32 v[72:73], v[2:3], v[24:25], v[72:73] op_sel:[0,1,0] op_sel_hi:[1,0,1]
	s_nop 0
	v_pk_fma_f32 v[24:25], v[0:1], v[24:25], v[72:73]
	s_cmp_eq_u32 s0, 12
	s_cbranch_scc1 .LBB0_167
	v_pk_fma_f32 v[74:75], v[2:3], v[24:25], v[74:75] op_sel:[0,1,0] op_sel_hi:[1,0,1]
	s_nop 0
	v_pk_fma_f32 v[24:25], v[0:1], v[24:25], v[74:75]
	s_cmp_eq_u32 s0, 13
	s_cbranch_scc1 .LBB0_167
	v_pk_fma_f32 v[76:77], v[2:3], v[24:25], v[76:77] op_sel:[0,1,0] op_sel_hi:[1,0,1]
	s_nop 0
	v_pk_fma_f32 v[24:25], v[0:1], v[24:25], v[76:77]
	s_cmp_eq_u32 s0, 14
	s_cbranch_scc1 .LBB0_167
	v_pk_fma_f32 v[78:79], v[2:3], v[24:25], v[78:79] op_sel:[0,1,0] op_sel_hi:[1,0,1]
	s_nop 0
	v_pk_fma_f32 v[24:25], v[0:1], v[24:25], v[78:79]
	s_cmp_eq_u32 s0, 15
	s_cbranch_scc1 .LBB0_167
	v_pk_fma_f32 v[80:81], v[2:3], v[24:25], v[80:81] op_sel:[0,1,0] op_sel_hi:[1,0,1]
	s_nop 0
	v_pk_fma_f32 v[24:25], v[0:1], v[24:25], v[80:81]
	s_cmp_eq_u32 s0, 16
	s_cbranch_scc1 .LBB0_167
	v_pk_fma_f32 v[82:83], v[2:3], v[24:25], v[82:83] op_sel:[0,1,0] op_sel_hi:[1,0,1]
	s_nop 0
	v_pk_fma_f32 v[24:25], v[0:1], v[24:25], v[82:83]
	s_cmp_eq_u32 s0, 17
	s_cbranch_scc1 .LBB0_167
	v_pk_fma_f32 v[84:85], v[2:3], v[24:25], v[84:85] op_sel:[0,1,0] op_sel_hi:[1,0,1]
	s_nop 0
	v_pk_fma_f32 v[24:25], v[0:1], v[24:25], v[84:85]
	s_cmp_eq_u32 s0, 18
	s_cbranch_scc1 .LBB0_167
	v_pk_fma_f32 v[86:87], v[2:3], v[24:25], v[86:87] op_sel:[0,1,0] op_sel_hi:[1,0,1]
	s_nop 0
	v_pk_fma_f32 v[24:25], v[0:1], v[24:25], v[86:87]
	s_cmp_eq_u32 s0, 19
	s_cbranch_scc1 .LBB0_167
	v_pk_fma_f32 v[88:89], v[2:3], v[24:25], v[88:89] op_sel:[0,1,0] op_sel_hi:[1,0,1]
	s_nop 0
	v_pk_fma_f32 v[24:25], v[0:1], v[24:25], v[88:89]
	s_cmp_eq_u32 s0, 20
	s_cbranch_scc1 .LBB0_167
	v_pk_fma_f32 v[90:91], v[2:3], v[24:25], v[90:91] op_sel:[0,1,0] op_sel_hi:[1,0,1]
	s_nop 0
	v_pk_fma_f32 v[24:25], v[0:1], v[24:25], v[90:91]
	s_cmp_eq_u32 s0, 21
	s_cbranch_scc1 .LBB0_167
	v_pk_fma_f32 v[92:93], v[2:3], v[24:25], v[92:93] op_sel:[0,1,0] op_sel_hi:[1,0,1]
	s_nop 0
	v_pk_fma_f32 v[24:25], v[0:1], v[24:25], v[92:93]
	s_cmp_eq_u32 s0, 22
	s_cbranch_scc1 .LBB0_167
	v_pk_fma_f32 v[94:95], v[2:3], v[24:25], v[94:95] op_sel:[0,1,0] op_sel_hi:[1,0,1]
	s_nop 0
	v_pk_fma_f32 v[24:25], v[0:1], v[24:25], v[94:95]
	s_cmp_eq_u32 s0, 23
	s_cbranch_scc1 .LBB0_167
	v_pk_fma_f32 v[96:97], v[2:3], v[24:25], v[96:97] op_sel:[0,1,0] op_sel_hi:[1,0,1]
	s_nop 0
	v_pk_fma_f32 v[24:25], v[0:1], v[24:25], v[96:97]
	s_cmp_eq_u32 s0, 24
	s_cbranch_scc1 .LBB0_167
	v_pk_fma_f32 v[98:99], v[2:3], v[24:25], v[98:99] op_sel:[0,1,0] op_sel_hi:[1,0,1]
	s_nop 0
	v_pk_fma_f32 v[24:25], v[0:1], v[24:25], v[98:99]
	s_cmp_eq_u32 s0, 25
	s_cbranch_scc1 .LBB0_167
	v_pk_fma_f32 v[100:101], v[2:3], v[24:25], v[100:101] op_sel:[0,1,0] op_sel_hi:[1,0,1]
	s_nop 0
	v_pk_fma_f32 v[24:25], v[0:1], v[24:25], v[100:101]
	s_cmp_eq_u32 s0, 26
	s_cbranch_scc1 .LBB0_167
	v_pk_fma_f32 v[102:103], v[2:3], v[24:25], v[102:103] op_sel:[0,1,0] op_sel_hi:[1,0,1]
	s_nop 0
	v_pk_fma_f32 v[24:25], v[0:1], v[24:25], v[102:103]
	s_cmp_eq_u32 s0, 27
	s_cbranch_scc1 .LBB0_167
	v_pk_fma_f32 v[104:105], v[2:3], v[24:25], v[104:105] op_sel:[0,1,0] op_sel_hi:[1,0,1]
	s_nop 0
	v_pk_fma_f32 v[24:25], v[0:1], v[24:25], v[104:105]
	s_cmp_eq_u32 s0, 28
	s_cbranch_scc1 .LBB0_167
	v_pk_fma_f32 v[106:107], v[2:3], v[24:25], v[106:107] op_sel:[0,1,0] op_sel_hi:[1,0,1]
	s_nop 0
	v_pk_fma_f32 v[24:25], v[0:1], v[24:25], v[106:107]
	s_cmp_eq_u32 s0, 29
	s_cbranch_scc1 .LBB0_167
; __device__ __forceinline__ void ssm_pass2(ArgP a, LAS unsigned char* lds, int l, const int tid, const int item) {
;     ...
;           for (; j + 8 <= chunk; j += 8) { f32x2e ev[8];
; #pragma unroll
;               for (int q = 0; q < 8; ++q) ev[q] = eb[(size_t)(j + q) * (32 * 64)];
; #pragma unroll
;               for (int q = 0; q < 8; ++q) { const float nr = fmaf(pr, wr_, fmaf(-pi, wi_, ev[q].x)), ni = fmaf(pr, wi_, fmaf(pi, wr_, ev[q].y)); wr_ = nr; wi_ = ni; } }
;           for (; j < chunk; ++j) { const f32x2e ev = eb[(size_t)j * (32 * 64)];
;               const float nr = fmaf(pr, wr_, fmaf(-pi, wi_, ev.x)), ni = fmaf(pr, wi_, fmaf(pi, wr_, ev.y)); wr_ = nr; wi_ = ni; } }
	v_pk_fma_f32 v[108:109], v[2:3], v[24:25], v[108:109] op_sel:[0,1,0] op_sel_hi:[1,0,1]
	s_nop 0
	v_pk_fma_f32 v[24:25], v[0:1], v[24:25], v[108:109]
	s_cmp_eq_u32 s0, 30
	s_cbranch_scc1 .LBB0_167
	v_pk_fma_f32 v[110:111], v[2:3], v[24:25], v[110:111] op_sel:[0,1,0] op_sel_hi:[1,0,1]
	s_nop 0
	v_pk_fma_f32 v[24:25], v[0:1], v[24:25], v[110:111]
	s_cmp_eq_u32 s0, 31
	s_cbranch_scc1 .LBB0_167
	v_pk_fma_f32 v[112:113], v[2:3], v[24:25], v[112:113] op_sel:[0,1,0] op_sel_hi:[1,0,1]
	s_nop 0
	v_pk_fma_f32 v[24:25], v[0:1], v[24:25], v[112:113]
	s_cmp_eq_u32 s0, 32
	s_cbranch_scc1 .LBB0_167
	v_pk_fma_f32 v[114:115], v[2:3], v[24:25], v[114:115] op_sel:[0,1,0] op_sel_hi:[1,0,1]
	s_nop 0
	v_pk_fma_f32 v[24:25], v[0:1], v[24:25], v[114:115]
	s_cmp_eq_u32 s0, 33
	s_cbranch_scc1 .LBB0_167
	v_pk_fma_f32 v[116:117], v[2:3], v[24:25], v[116:117] op_sel:[0,1,0] op_sel_hi:[1,0,1]
	s_nop 0
	v_pk_fma_f32 v[24:25], v[0:1], v[24:25], v[116:117]
	s_cmp_eq_u32 s0, 34
	s_cbranch_scc1 .LBB0_167
	v_pk_fma_f32 v[118:119], v[2:3], v[24:25], v[118:119] op_sel:[0,1,0] op_sel_hi:[1,0,1]
	s_nop 0
	v_pk_fma_f32 v[24:25], v[0:1], v[24:25], v[118:119]
	s_cmp_eq_u32 s0, 35
	s_cbranch_scc1 .LBB0_167
	v_pk_fma_f32 v[120:121], v[2:3], v[24:25], v[120:121] op_sel:[0,1,0] op_sel_hi:[1,0,1]
	s_nop 0
	v_pk_fma_f32 v[24:25], v[0:1], v[24:25], v[120:121]
	s_cmp_eq_u32 s0, 36
	s_cbranch_scc1 .LBB0_167
	v_pk_fma_f32 v[122:123], v[2:3], v[24:25], v[122:123] op_sel:[0,1,0] op_sel_hi:[1,0,1]
	s_nop 0
	v_pk_fma_f32 v[24:25], v[0:1], v[24:25], v[122:123]
	s_cmp_eq_u32 s0, 37
	s_cbranch_scc1 .LBB0_167
	v_pk_fma_f32 v[124:125], v[2:3], v[24:25], v[124:125] op_sel:[0,1,0] op_sel_hi:[1,0,1]
	s_nop 0
	v_pk_fma_f32 v[24:25], v[0:1], v[24:25], v[124:125]
	s_cmp_eq_u32 s0, 38
	s_cbranch_scc1 .LBB0_167
	v_pk_fma_f32 v[126:127], v[2:3], v[24:25], v[126:127] op_sel:[0,1,0] op_sel_hi:[1,0,1]
	s_nop 0
	v_pk_fma_f32 v[24:25], v[0:1], v[24:25], v[126:127]
	s_cmp_eq_u32 s0, 39
	s_cbranch_scc1 .LBB0_167
	v_pk_fma_f32 v[128:129], v[2:3], v[24:25], v[128:129] op_sel:[0,1,0] op_sel_hi:[1,0,1]
	s_nop 0
	v_pk_fma_f32 v[24:25], v[0:1], v[24:25], v[128:129]
	s_cmp_eq_u32 s0, 40
	s_cbranch_scc1 .LBB0_167
	v_pk_fma_f32 v[130:131], v[2:3], v[24:25], v[130:131] op_sel:[0,1,0] op_sel_hi:[1,0,1]
	s_nop 0
	v_pk_fma_f32 v[24:25], v[0:1], v[24:25], v[130:131]
	s_cmp_eq_u32 s0, 41
	s_cbranch_scc1 .LBB0_167
	v_pk_fma_f32 v[132:133], v[2:3], v[24:25], v[132:133] op_sel:[0,1,0] op_sel_hi:[1,0,1]
	s_nop 0
	v_pk_fma_f32 v[24:25], v[0:1], v[24:25], v[132:133]
	s_cmp_eq_u32 s0, 42
	s_cbranch_scc1 .LBB0_167
	v_pk_fma_f32 v[134:135], v[2:3], v[24:25], v[134:135] op_sel:[0,1,0] op_sel_hi:[1,0,1]
	s_nop 0
	v_pk_fma_f32 v[24:25], v[0:1], v[24:25], v[134:135]
	s_cmp_eq_u32 s0, 43
	s_cbranch_scc1 .LBB0_167
	v_pk_fma_f32 v[136:137], v[2:3], v[24:25], v[136:137] op_sel:[0,1,0] op_sel_hi:[1,0,1]
	s_nop 0
	v_pk_fma_f32 v[24:25], v[0:1], v[24:25], v[136:137]
	s_cmp_eq_u32 s0, 44
	s_cbranch_scc1 .LBB0_167
	v_pk_fma_f32 v[138:139], v[2:3], v[24:25], v[138:139] op_sel:[0,1,0] op_sel_hi:[1,0,1]
	s_nop 0
	v_pk_fma_f32 v[24:25], v[0:1], v[24:25], v[138:139]
	s_cmp_eq_u32 s0, 45
	s_cbranch_scc1 .LBB0_167
	v_pk_fma_f32 v[140:141], v[2:3], v[24:25], v[140:141] op_sel:[0,1,0] op_sel_hi:[1,0,1]
	s_nop 0
	v_pk_fma_f32 v[24:25], v[0:1], v[24:25], v[140:141]
	s_cmp_eq_u32 s0, 46
	s_cbranch_scc1 .LBB0_167
	v_pk_fma_f32 v[142:143], v[2:3], v[24:25], v[142:143] op_sel:[0,1,0] op_sel_hi:[1,0,1]
	s_nop 0
	v_pk_fma_f32 v[24:25], v[0:1], v[24:25], v[142:143]
	s_cmp_eq_u32 s0, 47
	s_cbranch_scc1 .LBB0_167
	v_pk_fma_f32 v[146:147], v[2:3], v[24:25], v[146:147] op_sel:[0,1,0] op_sel_hi:[1,0,1]
	s_nop 0
	v_pk_fma_f32 v[24:25], v[0:1], v[24:25], v[146:147]
	s_cmp_eq_u32 s0, 48
	s_cbranch_scc1 .LBB0_167
	v_pk_fma_f32 v[148:149], v[2:3], v[24:25], v[148:149] op_sel:[0,1,0] op_sel_hi:[1,0,1]
	s_nop 0
	v_pk_fma_f32 v[24:25], v[0:1], v[24:25], v[148:149]
	s_cmp_eq_u32 s0, 49
	s_cbranch_scc1 .LBB0_167
	v_pk_fma_f32 v[150:151], v[2:3], v[24:25], v[150:151] op_sel:[0,1,0] op_sel_hi:[1,0,1]
	s_nop 0
	v_pk_fma_f32 v[24:25], v[0:1], v[24:25], v[150:151]
	s_cmp_eq_u32 s0, 50
	s_cbranch_scc1 .LBB0_167
	v_pk_fma_f32 v[152:153], v[2:3], v[24:25], v[152:153] op_sel:[0,1,0] op_sel_hi:[1,0,1]
	s_nop 0
	v_pk_fma_f32 v[24:25], v[0:1], v[24:25], v[152:153]
	s_cmp_eq_u32 s0, 51
	s_cbranch_scc1 .LBB0_167
	v_pk_fma_f32 v[154:155], v[2:3], v[24:25], v[154:155] op_sel:[0,1,0] op_sel_hi:[1,0,1]
	s_nop 0
	v_pk_fma_f32 v[24:25], v[0:1], v[24:25], v[154:155]
	s_cmp_eq_u32 s0, 52
	s_cbranch_scc1 .LBB0_167
	v_pk_fma_f32 v[156:157], v[2:3], v[24:25], v[156:157] op_sel:[0,1,0] op_sel_hi:[1,0,1]
	s_nop 0
	v_pk_fma_f32 v[24:25], v[0:1], v[24:25], v[156:157]
	s_cmp_eq_u32 s0, 53
	s_cbranch_scc1 .LBB0_167
	v_pk_fma_f32 v[158:159], v[2:3], v[24:25], v[158:159] op_sel:[0,1,0] op_sel_hi:[1,0,1]
	s_nop 0
	v_pk_fma_f32 v[24:25], v[0:1], v[24:25], v[158:159]
	s_cmp_eq_u32 s0, 54
	s_cbranch_scc1 .LBB0_167
	v_pk_fma_f32 v[160:161], v[2:3], v[24:25], v[160:161] op_sel:[0,1,0] op_sel_hi:[1,0,1]
	s_nop 0
	v_pk_fma_f32 v[24:25], v[0:1], v[24:25], v[160:161]
	s_cmp_eq_u32 s0, 55
	s_cbranch_scc1 .LBB0_167
	v_pk_fma_f32 v[162:163], v[2:3], v[24:25], v[162:163] op_sel:[0,1,0] op_sel_hi:[1,0,1]
	s_nop 0
	v_pk_fma_f32 v[24:25], v[0:1], v[24:25], v[162:163]
	s_cmp_eq_u32 s0, 56
	s_cbranch_scc1 .LBB0_167
	v_pk_fma_f32 v[164:165], v[2:3], v[24:25], v[164:165] op_sel:[0,1,0] op_sel_hi:[1,0,1]
	s_nop 0
	v_pk_fma_f32 v[24:25], v[0:1], v[24:25], v[164:165]
	s_cmp_eq_u32 s0, 57
	s_cbranch_scc1 .LBB0_167
	v_pk_fma_f32 v[166:167], v[2:3], v[24:25], v[166:167] op_sel:[0,1,0] op_sel_hi:[1,0,1]
	s_nop 0
	v_pk_fma_f32 v[24:25], v[0:1], v[24:25], v[166:167]
	s_cmp_eq_u32 s0, 58
	s_cbranch_scc1 .LBB0_167
	v_pk_fma_f32 v[168:169], v[2:3], v[24:25], v[168:169] op_sel:[0,1,0] op_sel_hi:[1,0,1]
	s_nop 0
	v_pk_fma_f32 v[24:25], v[0:1], v[24:25], v[168:169]
	s_cmp_eq_u32 s0, 59
	s_cbranch_scc1 .LBB0_167
	v_pk_fma_f32 v[170:171], v[2:3], v[24:25], v[170:171] op_sel:[0,1,0] op_sel_hi:[1,0,1]
	s_nop 0
	v_pk_fma_f32 v[24:25], v[0:1], v[24:25], v[170:171]
	s_cmp_eq_u32 s0, 60
	s_cbranch_scc1 .LBB0_167
	v_pk_fma_f32 v[172:173], v[2:3], v[24:25], v[172:173] op_sel:[0,1,0] op_sel_hi:[1,0,1]
	s_nop 0
	v_pk_fma_f32 v[24:25], v[0:1], v[24:25], v[172:173]
	s_cmp_eq_u32 s0, 61
	s_cbranch_scc1 .LBB0_167
	v_pk_fma_f32 v[174:175], v[2:3], v[24:25], v[174:175] op_sel:[0,1,0] op_sel_hi:[1,0,1]
	s_nop 0
	v_pk_fma_f32 v[24:25], v[0:1], v[24:25], v[174:175]
	s_cmp_eq_u32 s0, 62
	s_cbranch_scc1 .LBB0_167
	v_pk_fma_f32 v[176:177], v[2:3], v[24:25], v[176:177] op_sel:[0,1,0] op_sel_hi:[1,0,1]
	s_nop 0
	v_pk_fma_f32 v[24:25], v[0:1], v[24:25], v[176:177]
	s_branch .LBB0_167
; __device__ __forceinline__ unsigned cvt_pk_bf16(float lo, float hi) { unsigned r; asm volatile("v_cvt_pk_bf16_f32 %0, %1, %2" : "=v"(r) : "v"(lo), "v"(hi)); return r; }
; __device__ __forceinline__ void ssm_cfrag(ArgP a, int l, int g, int fr, int fq, bf16x8* cf) {
; #pragma unroll
;     for (int ks = 0; ks < 4; ++ks) {
;         const float* src = (ks < 2 ? a->c_re : a->c_im) + (((size_t)l * 32 + g) * 16 + fr) * 64 + (ks & 1) * 32 + fq * 8;
;         const f32x4 c0 = *(const f32x4*)src, c1 = *(const f32x4*)(src + 4); const float sg = ks < 2 ? 1.f : -1.f;
;         u32x4 w; w.x = cvt_pk_bf16(sg * c0[0], sg * c0[1]); w.y = cvt_pk_bf16(sg * c0[2], sg * c0[3]); w.z = cvt_pk_bf16(sg * c1[0], sg * c1[1]); w.w = cvt_pk_bf16(sg * c1[2], sg * c1[3]);
;         cf[ks] = *reinterpret_cast<bf16x8*>(&w);
;     }
; }
; __device__ __forceinline__ void ssm_pass2(ArgP a, LAS unsigned char* lds, int l, const int tid, const int item) {
;     ...
;         bf16x8 cf[4]; ssm_cfrag(a, l, g, fr, fq, cf);
;         for (int sb = 0; sb < SSM_CH / 16; ++sb) {
;             const int tb = t0 + sb * 16;
;             float yl[4];
; #pragma unroll
;             for (int j = 0; j < 4; ++j) yl[j] = YL[(size_t)(tb + fq * 4 + j) * 512 + g * 16 + fr];
.LBB0_163:
	s_cbranch_execnz .LBB0_118
	s_branch .LBB0_151
.LBB0_167:
	s_lshl_b32 s1, s4, 13
	s_add_i32 s1, s1, 0
	s_lshl_b64 s[4:5], s[2:3], 4
	s_add_u32 s3, s4, s24
	s_addc_u32 s4, s5, s25
	v_mov_b32_e32 v1, s4
	v_readlane_b32 s4, v255, 23
	v_readlane_b32 s5, v255, 24
	s_load_dwordx4 s[8:11], s[4:5], 0x68
	v_and_b32_e32 v17, 15, v144
	v_or_b32_e32 v0, s3, v17
	v_lshrrev_b32_e32 v18, 4, v16
	v_lshlrev_b64 v[14:15], 8, v[0:1]
	s_waitcnt lgkmcnt(0)
	v_lshl_add_u64 v[0:1], s[8:9], 0, v[14:15]
	v_lshlrev_b32_e32 v180, 5, v18
	v_lshl_add_u64 v[10:11], v[0:1], 0, v[180:181]
	global_load_dwordx4 v[2:5], v[10:11], off offset:16
	global_load_dwordx4 v[6:9], v[10:11], off
	s_lshl_b32 s2, s2, 4
	s_ashr_i32 s3, s2, 31
	s_lshl_b64 s[4:5], s[2:3], 2
	s_add_u32 s4, s40, s4
	s_addc_u32 s5, s41, s5
	v_mov_b32_e32 v23, s1
	v_lshlrev_b32_e32 v21, 2, v18
	v_and_b32_e32 v30, 48, v144
	v_lshl_or_b32 v38, s0, 8, v21
	v_mov_b32_e32 v21, v20
	v_lshl_add_u32 v39, v16, 1, s1
	s_mov_b32 s1, 0
	s_waitcnt vmcnt(0)
	v_cvt_pk_bf16_f32 v0, v6, v7
	v_cvt_pk_bf16_f32 v1, v8, v9
	v_cvt_pk_bf16_f32 v2, v2, v3
	v_cvt_pk_bf16_f32 v3, v4, v5
	global_load_dwordx4 v[6:9], v[10:11], off offset:144
	s_nop 0
	global_load_dwordx4 v[10:13], v[10:11], off offset:128
	s_waitcnt vmcnt(0)
	v_cvt_pk_bf16_f32 v4, v10, v11
	v_cvt_pk_bf16_f32 v5, v12, v13
	v_cvt_pk_bf16_f32 v6, v6, v7
	v_cvt_pk_bf16_f32 v7, v8, v9
	v_lshl_add_u64 v[8:9], s[10:11], 0, v[14:15]
	v_lshl_add_u64 v[14:15], v[8:9], 0, v[180:181]
	global_load_dwordx4 v[10:13], v[14:15], off offset:16
	global_load_dwordx4 v[26:29], v[14:15], off
	v_lshlrev_b32_e32 v180, 2, v17
	s_waitcnt vmcnt(1)
	v_xor_b32_e32 v10, 0x80000000, v10
	s_waitcnt vmcnt(0)
	v_xor_b32_e32 v8, 0x80000000, v26
	v_xor_b32_e32 v9, 0x80000000, v27
	v_cvt_pk_bf16_f32 v8, v8, v9
	v_xor_b32_e32 v9, 0x80000000, v28
	v_xor_b32_e32 v11, 0x80000000, v11
	v_xor_b32_e32 v19, 0x80000000, v29
	v_cvt_pk_bf16_f32 v9, v9, v19
	v_cvt_pk_bf16_f32 v10, v10, v11
	v_xor_b32_e32 v11, 0x80000000, v12
	v_xor_b32_e32 v12, 0x80000000, v13
	v_cvt_pk_bf16_f32 v11, v11, v12
	global_load_dwordx4 v[26:29], v[14:15], off offset:144
	s_nop 0
	global_load_dwordx4 v[12:15], v[14:15], off offset:128
	s_waitcnt vmcnt(1)
	v_xor_b32_e32 v19, 0x80000000, v29
	s_waitcnt vmcnt(0)
	v_xor_b32_e32 v12, 0x80000000, v12
	v_xor_b32_e32 v13, 0x80000000, v13
	v_cvt_pk_bf16_f32 v12, v12, v13
	v_xor_b32_e32 v13, 0x80000000, v14
	v_xor_b32_e32 v14, 0x80000000, v15
	v_cvt_pk_bf16_f32 v13, v13, v14
	v_xor_b32_e32 v14, 0x80000000, v26
	v_xor_b32_e32 v15, 0x80000000, v27
	v_cvt_pk_bf16_f32 v14, v14, v15
	v_xor_b32_e32 v15, 0x80000000, v28
	v_lshl_add_u64 v[26:27], s[4:5], 0, v[180:181]
	v_lshlrev_b32_e32 v180, 1, v17
	s_movk_i32 s4, 0x110
	v_cvt_pk_bf16_f32 v15, v15, v19
	v_lshl_add_u64 v[18:19], s[18:19], 0, v[180:181]
	v_mad_u32_u24 v17, v17, s4, v23
	v_lshl_add_u64 v[28:29], s[2:3], 1, v[18:19]
	v_mov_b32_e32 v23, v22
	v_add_u32_e32 v40, v17, v30
